# peerq K-loops hand-written (LDS-DMA), K-start rotation phase derived from the tile row index so dynamic tile assignment stays deterministic; all 10 GEMM K-loops hand-written with 4-phase rotation
# baseline (speedup 1.0000x reference)
.LBB0_786:
	s_lshl_b32 s10, s48, 7
	s_xor_b64 s[46:47], s[50:51], -1
	s_or_b32 s50, s31, s10
	s_mov_b32 s51, s75
	s_lshl_b64 s[50:51], s[50:51], 11
	s_add_u32 s50, s54, s50
	s_addc_u32 s51, s55, s51
	s_waitcnt lgkmcnt(0)
	s_lshl_b32 s98, s30, 11
	s_add_u32 s98, s52, s98
	s_addc_u32 s99, s53, 0
	v_and_b32_e32 v222, 15, v0
	v_bfe_u32 v223, v0, 4, 2
	v_and_b32_e32 v141, 7, v222
	v_xor_b32_e32 v223, v223, v141
	v_lshlrev_b32_e32 v223, 4, v223
	v_lshl_or_b32 v223, v222, 7, v223
	v_bfe_u32 v222, v0, 7, 1
	v_lshl_or_b32 v140, v222, 13, v223
	v_bfe_u32 v222, v0, 6, 1
	v_lshl_or_b32 v216, v222, 13, v223
	v_or_b32_e32 v216, 0x4000, v216
	v_xor_b32_e32 v141, 64, v140
	v_xor_b32_e32 v217, 64, v216
	v_bfe_u32 v222, v0, 3, 3
	v_and_b32_e32 v223, 7, v0
	v_xor_b32_e32 v223, v223, v222
	v_lshlrev_b32_e32 v223, 4, v223
	v_lshl_or_b32 v223, v222, 11, v223
	v_lshrrev_b32_e32 v222, 6, v0
	v_and_b32_e32 v222, 3, v222
	v_lshl_or_b32 v218, v222, 16, v223
	v_add_u32_e32 v219, 0x3c00, v218
	v_add_u32_e32 v220, 0x7800, v218
	v_add_u32_e32 v221, 0xb400, v218
	v_lshlrev_b32_e32 v222, 12, v222
	s_nop 0
	v_readfirstlane_b32 s101, v222
	s_add_u32 s101, s101, 32
	v_mov_b32_e32 v86, 0
	v_mov_b32_e32 v87, 0
	v_mov_b32_e32 v88, 0
	v_mov_b32_e32 v89, 0
	v_mov_b32_e32 v82, 0
	v_mov_b32_e32 v83, 0
	v_mov_b32_e32 v84, 0
	v_mov_b32_e32 v85, 0
	v_mov_b32_e32 v78, 0
	v_mov_b32_e32 v79, 0
	v_mov_b32_e32 v80, 0
	v_mov_b32_e32 v81, 0
	v_mov_b32_e32 v74, 0
	v_mov_b32_e32 v75, 0
	v_mov_b32_e32 v76, 0
	v_mov_b32_e32 v77, 0
	v_mov_b32_e32 v70, 0
	v_mov_b32_e32 v71, 0
	v_mov_b32_e32 v72, 0
	v_mov_b32_e32 v73, 0
	v_mov_b32_e32 v90, 0
	v_mov_b32_e32 v91, 0
	v_mov_b32_e32 v92, 0
	v_mov_b32_e32 v93, 0
	v_mov_b32_e32 v94, 0
	v_mov_b32_e32 v95, 0
	v_mov_b32_e32 v96, 0
	v_mov_b32_e32 v97, 0
	v_mov_b32_e32 v6, 0
	v_mov_b32_e32 v7, 0
	v_mov_b32_e32 v8, 0
	v_mov_b32_e32 v9, 0
	v_mov_b32_e32 v2, 0
	v_mov_b32_e32 v3, 0
	v_mov_b32_e32 v4, 0
	v_mov_b32_e32 v5, 0
	v_mov_b32_e32 v10, 0
	v_mov_b32_e32 v11, 0
	v_mov_b32_e32 v12, 0
	v_mov_b32_e32 v13, 0
	v_mov_b32_e32 v14, 0
	v_mov_b32_e32 v15, 0
	v_mov_b32_e32 v16, 0
	v_mov_b32_e32 v17, 0
	v_mov_b32_e32 v26, 0
	v_mov_b32_e32 v27, 0
	v_mov_b32_e32 v28, 0
	v_mov_b32_e32 v29, 0
	v_mov_b32_e32 v34, 0
	v_mov_b32_e32 v35, 0
	v_mov_b32_e32 v36, 0
	v_mov_b32_e32 v37, 0
	v_mov_b32_e32 v30, 0
	v_mov_b32_e32 v31, 0
	v_mov_b32_e32 v32, 0
	v_mov_b32_e32 v33, 0
	v_mov_b32_e32 v22, 0
	v_mov_b32_e32 v23, 0
	v_mov_b32_e32 v24, 0
	v_mov_b32_e32 v25, 0
	v_mov_b32_e32 v18, 0
	v_mov_b32_e32 v19, 0
	v_mov_b32_e32 v20, 0
	v_mov_b32_e32 v21, 0
	v_mov_b32_e32 v136, 0
	v_mov_b32_e32 v137, 0
	v_mov_b32_e32 v138, 0
	v_mov_b32_e32 v139, 0
	v_mov_b32_e32 v188, 0
	v_mov_b32_e32 v189, 0
	v_mov_b32_e32 v190, 0
	v_mov_b32_e32 v191, 0
	v_mov_b32_e32 v192, 0
	v_mov_b32_e32 v193, 0
	v_mov_b32_e32 v194, 0
	v_mov_b32_e32 v195, 0
	v_mov_b32_e32 v196, 0
	v_mov_b32_e32 v197, 0
	v_mov_b32_e32 v198, 0
	v_mov_b32_e32 v199, 0
	v_mov_b32_e32 v200, 0
	v_mov_b32_e32 v201, 0
	v_mov_b32_e32 v202, 0
	v_mov_b32_e32 v203, 0
	v_mov_b32_e32 v204, 0
	v_mov_b32_e32 v205, 0
	v_mov_b32_e32 v206, 0
	v_mov_b32_e32 v207, 0
	v_mov_b32_e32 v208, 0
	v_mov_b32_e32 v209, 0
	v_mov_b32_e32 v210, 0
	v_mov_b32_e32 v211, 0
	v_mov_b32_e32 v212, 0
	v_mov_b32_e32 v213, 0
	v_mov_b32_e32 v214, 0
	v_mov_b32_e32 v215, 0
	s_waitcnt lgkmcnt(0)
	s_barrier
	s_lshr_b32 s49, s30, 10
	s_and_b32 s49, s49, 3
	s_lshl_b32 s49, s49, 2
	s_lshl_b32 s10, s49, 7
	s_add_u32 s98, s98, s10
	s_addc_u32 s99, s99, 0
	s_add_u32 s50, s50, s10
	s_addc_u32 s51, s51, 0
	s_add_u32 m0, s101, 0
	s_nop 0
	global_load_lds_dwordx4 v218, s[98:99] offset:0
	global_load_lds_dwordx4 v219, s[98:99] offset:1024
	global_load_lds_dwordx4 v220, s[98:99] offset:2048
	global_load_lds_dwordx4 v221, s[98:99] offset:3072
	s_add_u32 m0, s101, 16384
	s_nop 0
	global_load_lds_dwordx4 v218, s[50:51] offset:0
	global_load_lds_dwordx4 v219, s[50:51] offset:1024
	global_load_lds_dwordx4 v220, s[50:51] offset:2048
	global_load_lds_dwordx4 v221, s[50:51] offset:3072
	s_add_u32 s49, s49, 1
	s_and_b32 s49, s49, 15
	s_cmp_eq_u32 s49, 0
	s_cselect_b32 s10, 0x800, 0
	s_add_u32 s98, s98, 0x80
	s_addc_u32 s99, s99, 0
	s_sub_u32 s98, s98, s10
	s_subb_u32 s99, s99, 0
	s_add_u32 s50, s50, 0x80
	s_addc_u32 s51, s51, 0
	s_sub_u32 s50, s50, s10
	s_subb_u32 s51, s51, 0
	s_mov_b32 s100, 0
	s_waitcnt vmcnt(0)

.LBB0_1496:
	s_lshl_b32 s10, s50, 7
	s_or_b32 s46, s37, s10
	s_xor_b64 s[48:49], s[52:53], -1
	s_lshl_b64 s[52:53], s[46:47], 11
	s_add_u32 s52, s55, s52
	s_addc_u32 s53, s56, s53
	s_waitcnt lgkmcnt(0)
	s_lshl_b32 s98, s36, 11
	s_add_u32 s98, s33, s98
	s_addc_u32 s99, s54, 0
	v_and_b32_e32 v212, 15, v0
	v_bfe_u32 v213, v0, 4, 2
	v_and_b32_e32 v139, 7, v212
	v_xor_b32_e32 v213, v213, v139
	v_lshlrev_b32_e32 v213, 4, v213
	v_lshl_or_b32 v213, v212, 7, v213
	v_bfe_u32 v212, v0, 7, 1
	v_lshl_or_b32 v138, v212, 13, v213
	v_bfe_u32 v212, v0, 6, 1
	v_lshl_or_b32 v206, v212, 13, v213
	v_or_b32_e32 v206, 0x4000, v206
	v_xor_b32_e32 v139, 64, v138
	v_xor_b32_e32 v207, 64, v206
	v_bfe_u32 v212, v0, 3, 3
	v_and_b32_e32 v213, 7, v0
	v_xor_b32_e32 v213, v213, v212
	v_lshlrev_b32_e32 v213, 4, v213
	v_lshl_or_b32 v213, v212, 11, v213
	v_lshrrev_b32_e32 v212, 6, v0
	v_and_b32_e32 v212, 3, v212
	v_lshl_or_b32 v208, v212, 16, v213
	v_add_u32_e32 v209, 0x3c00, v208
	v_add_u32_e32 v210, 0x7800, v208
	v_add_u32_e32 v211, 0xb400, v208
	v_lshlrev_b32_e32 v212, 12, v212
	s_nop 0
	v_readfirstlane_b32 s101, v212
	s_add_u32 s101, s101, 32
	v_mov_b32_e32 v66, 0
	v_mov_b32_e32 v67, 0
	v_mov_b32_e32 v68, 0
	v_mov_b32_e32 v69, 0
	v_mov_b32_e32 v58, 0
	v_mov_b32_e32 v59, 0
	v_mov_b32_e32 v60, 0
	v_mov_b32_e32 v61, 0
	v_mov_b32_e32 v54, 0
	v_mov_b32_e32 v55, 0
	v_mov_b32_e32 v56, 0
	v_mov_b32_e32 v57, 0
	v_mov_b32_e32 v50, 0
	v_mov_b32_e32 v51, 0
	v_mov_b32_e32 v52, 0
	v_mov_b32_e32 v53, 0
	v_mov_b32_e32 v46, 0
	v_mov_b32_e32 v47, 0
	v_mov_b32_e32 v48, 0
	v_mov_b32_e32 v49, 0
	v_mov_b32_e32 v42, 0
	v_mov_b32_e32 v43, 0
	v_mov_b32_e32 v44, 0
	v_mov_b32_e32 v45, 0
	v_mov_b32_e32 v38, 0
	v_mov_b32_e32 v39, 0
	v_mov_b32_e32 v40, 0
	v_mov_b32_e32 v41, 0
	v_mov_b32_e32 v6, 0
	v_mov_b32_e32 v7, 0
	v_mov_b32_e32 v8, 0
	v_mov_b32_e32 v9, 0
	v_mov_b32_e32 v2, 0
	v_mov_b32_e32 v3, 0
	v_mov_b32_e32 v4, 0
	v_mov_b32_e32 v5, 0
	v_mov_b32_e32 v22, 0
	v_mov_b32_e32 v23, 0
	v_mov_b32_e32 v24, 0
	v_mov_b32_e32 v25, 0
	v_mov_b32_e32 v18, 0
	v_mov_b32_e32 v19, 0
	v_mov_b32_e32 v20, 0
	v_mov_b32_e32 v21, 0
	v_mov_b32_e32 v14, 0
	v_mov_b32_e32 v15, 0
	v_mov_b32_e32 v16, 0
	v_mov_b32_e32 v17, 0
	v_mov_b32_e32 v10, 0
	v_mov_b32_e32 v11, 0
	v_mov_b32_e32 v12, 0
	v_mov_b32_e32 v13, 0
	v_mov_b32_e32 v34, 0
	v_mov_b32_e32 v35, 0
	v_mov_b32_e32 v36, 0
	v_mov_b32_e32 v37, 0
	v_mov_b32_e32 v30, 0
	v_mov_b32_e32 v31, 0
	v_mov_b32_e32 v32, 0
	v_mov_b32_e32 v33, 0
	v_mov_b32_e32 v26, 0
	v_mov_b32_e32 v27, 0
	v_mov_b32_e32 v28, 0
	v_mov_b32_e32 v29, 0
	v_mov_b32_e32 v134, 0
	v_mov_b32_e32 v135, 0
	v_mov_b32_e32 v136, 0
	v_mov_b32_e32 v137, 0
	v_mov_b32_e32 v178, 0
	v_mov_b32_e32 v179, 0
	v_mov_b32_e32 v180, 0
	v_mov_b32_e32 v181, 0
	v_mov_b32_e32 v182, 0
	v_mov_b32_e32 v183, 0
	v_mov_b32_e32 v184, 0
	v_mov_b32_e32 v185, 0
	v_mov_b32_e32 v186, 0
	v_mov_b32_e32 v187, 0
	v_mov_b32_e32 v188, 0
	v_mov_b32_e32 v189, 0
	v_mov_b32_e32 v190, 0
	v_mov_b32_e32 v191, 0
	v_mov_b32_e32 v192, 0
	v_mov_b32_e32 v193, 0
	v_mov_b32_e32 v194, 0
	v_mov_b32_e32 v195, 0
	v_mov_b32_e32 v196, 0
	v_mov_b32_e32 v197, 0
	v_mov_b32_e32 v198, 0
	v_mov_b32_e32 v199, 0
	v_mov_b32_e32 v200, 0
	v_mov_b32_e32 v201, 0
	v_mov_b32_e32 v202, 0
	v_mov_b32_e32 v203, 0
	v_mov_b32_e32 v204, 0
	v_mov_b32_e32 v205, 0
	s_waitcnt lgkmcnt(0)
	s_barrier
	s_lshr_b32 s46, s36, 10
	s_and_b32 s46, s46, 3
	s_lshl_b32 s46, s46, 2
	s_lshl_b32 s51, s46, 7
	s_add_u32 s98, s98, s51
	s_addc_u32 s99, s99, 0
	s_add_u32 s52, s52, s51
	s_addc_u32 s53, s53, 0
	s_add_u32 m0, s101, 0
	s_nop 0
	global_load_lds_dwordx4 v208, s[98:99] offset:0
	global_load_lds_dwordx4 v209, s[98:99] offset:1024
	global_load_lds_dwordx4 v210, s[98:99] offset:2048
	global_load_lds_dwordx4 v211, s[98:99] offset:3072
	s_add_u32 m0, s101, 16384
	s_nop 0
	global_load_lds_dwordx4 v208, s[52:53] offset:0
	global_load_lds_dwordx4 v209, s[52:53] offset:1024
	global_load_lds_dwordx4 v210, s[52:53] offset:2048
	global_load_lds_dwordx4 v211, s[52:53] offset:3072
	s_add_u32 s46, s46, 1
	s_and_b32 s46, s46, 15
	s_cmp_eq_u32 s46, 0
	s_cselect_b32 s51, 0x800, 0
	s_add_u32 s98, s98, 0x80
	s_addc_u32 s99, s99, 0
	s_sub_u32 s98, s98, s51
	s_subb_u32 s99, s99, 0
	s_add_u32 s52, s52, 0x80
	s_addc_u32 s53, s53, 0
	s_sub_u32 s52, s52, s51
	s_subb_u32 s53, s53, 0
	s_mov_b32 s100, 0
	s_waitcnt vmcnt(0)
